# GEMM K-loops: the address VALU at the head of the 6-DMA load segments moved behind the segment's LDS fragment reads
# baseline (speedup 1.0000x reference)
.LBB0_169:
	s_add_u32 s42, s40, 0xfff80080
	s_addc_u32 s43, s41, -1
	s_add_i32 s52, 0, 0x10000
	s_cmp_eq_u32 s51, 28
	s_cselect_b32 s45, s13, s43
	s_cselect_b32 s44, s47, s42
	s_cselect_b32 s43, s11, s50
	s_cselect_b32 s42, s48, s49
	s_add_i32 s54, 0, 0x14000
	ds_read_b128 v[130:133], v236
	ds_read_b128 v[134:137], v236 offset:1024
	ds_read_b128 v[138:141], v236 offset:2048
	ds_read_b128 v[142:145], v236 offset:3072
	ds_read_b128 v[170:173], v237
	ds_read_b128 v[184:187], v237 offset:1024
	ds_read_b128 v[188:191], v237 offset:2048
	ds_read_b128 v[192:195], v237 offset:3072
	s_add_i32 m0, s14, 0xc000
	ds_read_b128 v[196:199], v183
	ds_read_b128 v[200:203], v183 offset:1024
	ds_read_b128 v[210:213], v183 offset:2048
	ds_read_b128 v[214:217], v183 offset:3072
	ds_read_b128 v[218:221], v183 offset:4096
	ds_read_b128 v[222:225], v183 offset:5120
	ds_read_b128 v[226:229], v183 offset:6144
	ds_read_b128 v[230:233], v183 offset:7168
	global_load_lds_dwordx4 v166, s[40:41]
	s_add_i32 m0, s14, 0xe000
	s_nop 0
	global_load_lds_dwordx4 v168, s[40:41]
	s_waitcnt vmcnt(8) lgkmcnt(0)
	s_barrier
	v_mfma_f32_16x16x32_bf16 v[126:129], v[130:133], v[196:199], v[126:129]
	v_mfma_f32_16x16x32_bf16 v[122:125], v[138:141], v[196:199], v[122:125]
	v_mfma_f32_16x16x32_bf16 v[118:121], v[130:133], v[210:213], v[118:121]
	v_mfma_f32_16x16x32_bf16 v[110:113], v[138:141], v[210:213], v[110:113]
	v_mfma_f32_16x16x32_bf16 v[102:105], v[130:133], v[218:221], v[102:105]
	v_mfma_f32_16x16x32_bf16 v[94:97], v[138:141], v[218:221], v[94:97]
	v_mfma_f32_16x16x32_bf16 v[86:89], v[130:133], v[226:229], v[86:89]
	v_mfma_f32_16x16x32_bf16 v[78:81], v[138:141], v[226:229], v[78:81]
	v_mfma_f32_16x16x32_bf16 v[126:129], v[134:137], v[200:203], v[126:129]
	v_mfma_f32_16x16x32_bf16 v[122:125], v[142:145], v[200:203], v[122:125]
	v_mfma_f32_16x16x32_bf16 v[118:121], v[134:137], v[214:217], v[118:121]
	v_mfma_f32_16x16x32_bf16 v[110:113], v[142:145], v[214:217], v[110:113]
	v_mfma_f32_16x16x32_bf16 v[102:105], v[134:137], v[222:225], v[102:105]
	v_mfma_f32_16x16x32_bf16 v[94:97], v[142:145], v[222:225], v[94:97]
	v_mfma_f32_16x16x32_bf16 v[86:89], v[134:137], v[230:233], v[86:89]
	v_mfma_f32_16x16x32_bf16 v[78:81], v[142:145], v[230:233], v[78:81]
	v_mfma_f32_16x16x32_bf16 v[114:117], v[170:173], v[196:199], v[114:117]
	v_mfma_f32_16x16x32_bf16 v[106:109], v[188:191], v[196:199], v[106:109]
	v_mfma_f32_16x16x32_bf16 v[98:101], v[170:173], v[210:213], v[98:101]
	v_mfma_f32_16x16x32_bf16 v[90:93], v[188:191], v[210:213], v[90:93]
	v_mfma_f32_16x16x32_bf16 v[82:85], v[170:173], v[218:221], v[82:85]
	v_mfma_f32_16x16x32_bf16 v[74:77], v[188:191], v[218:221], v[74:77]
	v_mfma_f32_16x16x32_bf16 v[70:73], v[170:173], v[226:229], v[70:73]
	v_mfma_f32_16x16x32_bf16 v[66:69], v[188:191], v[226:229], v[66:69]
	v_mfma_f32_16x16x32_bf16 v[114:117], v[184:187], v[200:203], v[114:117]
	v_mfma_f32_16x16x32_bf16 v[106:109], v[192:195], v[200:203], v[106:109]
	v_mfma_f32_16x16x32_bf16 v[98:101], v[184:187], v[214:217], v[98:101]
	v_mfma_f32_16x16x32_bf16 v[90:93], v[192:195], v[214:217], v[90:93]
	v_mfma_f32_16x16x32_bf16 v[82:85], v[184:187], v[222:225], v[82:85]
	v_mfma_f32_16x16x32_bf16 v[74:77], v[192:195], v[222:225], v[74:77]
	v_mfma_f32_16x16x32_bf16 v[70:73], v[184:187], v[230:233], v[70:73]
	v_mfma_f32_16x16x32_bf16 v[66:69], v[192:195], v[230:233], v[66:69]
	s_barrier
	s_add_i32 s52, s52, s5
	s_mov_b32 m0, s52
	ds_read_b128 v[196:199], v183 offset:16384
	ds_read_b128 v[200:203], v183 offset:17408
	ds_read_b128 v[210:213], v183 offset:18432
	ds_read_b128 v[214:217], v183 offset:19456
	ds_read_b128 v[218:221], v183 offset:20480
	ds_read_b128 v[222:225], v183 offset:21504
	ds_read_b128 v[226:229], v183 offset:22528
	ds_read_b128 v[230:233], v183 offset:23552
	v_lshl_add_u64 v[154:155], s[42:43], 0, v[162:163]
	global_load_lds_dwordx4 v[154:155], off
	s_add_i32 m0, s52, 0x2000
	s_add_u32 s52, s42, 0x80000
	v_lshl_add_u64 v[156:157], s[42:43], 0, v[158:159]
	s_addc_u32 s53, s43, 0
	s_add_i32 s54, s54, s5
	global_load_lds_dwordx4 v[156:157], off
	s_mov_b32 m0, s54
	v_lshl_add_u64 v[180:181], s[44:45], 0, v[160:161]
	global_load_lds_dwordx4 v162, s[52:53]
	s_add_i32 m0, s54, 0x2000
	s_nop 0
	global_load_lds_dwordx4 v158, s[52:53]
	v_lshl_add_u64 v[176:177], s[44:45], 0, v[164:165]
	s_mov_b32 m0, s14
	s_nop 0
	global_load_lds_dwordx4 v[176:177], off
	s_mov_b32 m0, s15
	s_nop 0
	global_load_lds_dwordx4 v[180:181], off
	s_waitcnt vmcnt(8) lgkmcnt(0)
	s_barrier
	v_mfma_f32_16x16x32_bf16 v[62:65], v[130:133], v[196:199], v[62:65]
	v_mfma_f32_16x16x32_bf16 v[58:61], v[138:141], v[196:199], v[58:61]
	v_mfma_f32_16x16x32_bf16 v[54:57], v[130:133], v[210:213], v[54:57]
	v_mfma_f32_16x16x32_bf16 v[46:49], v[138:141], v[210:213], v[46:49]
	v_mfma_f32_16x16x32_bf16 v[38:41], v[130:133], v[218:221], v[38:41]
	v_mfma_f32_16x16x32_bf16 v[30:33], v[138:141], v[218:221], v[30:33]
	v_mfma_f32_16x16x32_bf16 v[22:25], v[130:133], v[226:229], v[22:25]
	v_mfma_f32_16x16x32_bf16 v[14:17], v[138:141], v[226:229], v[14:17]
	v_mfma_f32_16x16x32_bf16 v[62:65], v[134:137], v[200:203], v[62:65]
	v_mfma_f32_16x16x32_bf16 v[58:61], v[142:145], v[200:203], v[58:61]
	v_mfma_f32_16x16x32_bf16 v[54:57], v[134:137], v[214:217], v[54:57]
	v_mfma_f32_16x16x32_bf16 v[46:49], v[142:145], v[214:217], v[46:49]
	v_mfma_f32_16x16x32_bf16 v[38:41], v[134:137], v[222:225], v[38:41]
	v_mfma_f32_16x16x32_bf16 v[30:33], v[142:145], v[222:225], v[30:33]
	v_mfma_f32_16x16x32_bf16 v[22:25], v[134:137], v[230:233], v[22:25]
	v_mfma_f32_16x16x32_bf16 v[14:17], v[142:145], v[230:233], v[14:17]
	v_mfma_f32_16x16x32_bf16 v[50:53], v[170:173], v[196:199], v[50:53]
	v_mfma_f32_16x16x32_bf16 v[42:45], v[188:191], v[196:199], v[42:45]
	v_mfma_f32_16x16x32_bf16 v[34:37], v[170:173], v[210:213], v[34:37]
	v_mfma_f32_16x16x32_bf16 v[26:29], v[188:191], v[210:213], v[26:29]
	v_mfma_f32_16x16x32_bf16 v[18:21], v[170:173], v[218:221], v[18:21]
	v_mfma_f32_16x16x32_bf16 v[10:13], v[188:191], v[218:221], v[10:13]
	v_mfma_f32_16x16x32_bf16 v[6:9], v[170:173], v[226:229], v[6:9]
	v_mfma_f32_16x16x32_bf16 v[2:5], v[188:191], v[226:229], v[2:5]
	v_mfma_f32_16x16x32_bf16 v[50:53], v[184:187], v[200:203], v[50:53]
	v_mfma_f32_16x16x32_bf16 v[42:45], v[192:195], v[200:203], v[42:45]
	v_mfma_f32_16x16x32_bf16 v[34:37], v[184:187], v[214:217], v[34:37]
	v_mfma_f32_16x16x32_bf16 v[26:29], v[192:195], v[214:217], v[26:29]
	v_mfma_f32_16x16x32_bf16 v[18:21], v[184:187], v[222:225], v[18:21]
	v_mfma_f32_16x16x32_bf16 v[10:13], v[192:195], v[222:225], v[10:13]
	v_mfma_f32_16x16x32_bf16 v[6:9], v[184:187], v[230:233], v[6:9]
	v_mfma_f32_16x16x32_bf16 v[2:5], v[192:195], v[230:233], v[2:5]
	s_barrier
	s_add_i32 s52, 0, 0x18000
	s_add_i32 s53, 0, 0x1c000
	ds_read_b128 v[130:133], v238
	ds_read_b128 v[134:137], v238 offset:1024
	ds_read_b128 v[138:141], v238 offset:2048
	ds_read_b128 v[142:145], v238 offset:3072
	ds_read_b128 v[170:173], v239
	ds_read_b128 v[184:187], v239 offset:1024
	ds_read_b128 v[188:191], v239 offset:2048
	ds_read_b128 v[192:195], v239 offset:3072
	s_add_u32 s44, s44, 0x80000
	s_addc_u32 s45, s45, 0
	s_mov_b32 m0, s16
	ds_read_b128 v[196:199], v183 offset:32768
	ds_read_b128 v[200:203], v183 offset:33792
	ds_read_b128 v[210:213], v183 offset:34816
	ds_read_b128 v[214:217], v183 offset:35840
	ds_read_b128 v[218:221], v183 offset:36864
	ds_read_b128 v[222:225], v183 offset:37888
	ds_read_b128 v[226:229], v183 offset:38912
	ds_read_b128 v[230:233], v183 offset:39936
	global_load_lds_dwordx4 v164, s[44:45]
	s_mov_b32 m0, s18
	s_nop 0
	global_load_lds_dwordx4 v160, s[44:45]
	s_waitcnt vmcnt(8) lgkmcnt(0)
	s_barrier
	v_mfma_f32_16x16x32_bf16 v[126:129], v[130:133], v[196:199], v[126:129]
	v_mfma_f32_16x16x32_bf16 v[122:125], v[138:141], v[196:199], v[122:125]
	v_mfma_f32_16x16x32_bf16 v[118:121], v[130:133], v[210:213], v[118:121]
	v_mfma_f32_16x16x32_bf16 v[110:113], v[138:141], v[210:213], v[110:113]
	v_mfma_f32_16x16x32_bf16 v[102:105], v[130:133], v[218:221], v[102:105]
	v_mfma_f32_16x16x32_bf16 v[94:97], v[138:141], v[218:221], v[94:97]
	v_mfma_f32_16x16x32_bf16 v[86:89], v[130:133], v[226:229], v[86:89]
	v_mfma_f32_16x16x32_bf16 v[78:81], v[138:141], v[226:229], v[78:81]
	v_mfma_f32_16x16x32_bf16 v[126:129], v[134:137], v[200:203], v[126:129]
	v_mfma_f32_16x16x32_bf16 v[122:125], v[142:145], v[200:203], v[122:125]
	v_mfma_f32_16x16x32_bf16 v[118:121], v[134:137], v[214:217], v[118:121]
	v_mfma_f32_16x16x32_bf16 v[110:113], v[142:145], v[214:217], v[110:113]
	v_mfma_f32_16x16x32_bf16 v[102:105], v[134:137], v[222:225], v[102:105]
	v_mfma_f32_16x16x32_bf16 v[94:97], v[142:145], v[222:225], v[94:97]
	v_mfma_f32_16x16x32_bf16 v[86:89], v[134:137], v[230:233], v[86:89]
	v_mfma_f32_16x16x32_bf16 v[78:81], v[142:145], v[230:233], v[78:81]
	v_mfma_f32_16x16x32_bf16 v[114:117], v[170:173], v[196:199], v[114:117]
	v_mfma_f32_16x16x32_bf16 v[106:109], v[188:191], v[196:199], v[106:109]
	v_mfma_f32_16x16x32_bf16 v[98:101], v[170:173], v[210:213], v[98:101]
	v_mfma_f32_16x16x32_bf16 v[90:93], v[188:191], v[210:213], v[90:93]
	v_mfma_f32_16x16x32_bf16 v[82:85], v[170:173], v[218:221], v[82:85]
	v_mfma_f32_16x16x32_bf16 v[74:77], v[188:191], v[218:221], v[74:77]
	v_mfma_f32_16x16x32_bf16 v[70:73], v[170:173], v[226:229], v[70:73]
	v_mfma_f32_16x16x32_bf16 v[66:69], v[188:191], v[226:229], v[66:69]
	v_mfma_f32_16x16x32_bf16 v[114:117], v[184:187], v[200:203], v[114:117]
	v_mfma_f32_16x16x32_bf16 v[106:109], v[192:195], v[200:203], v[106:109]
	v_mfma_f32_16x16x32_bf16 v[98:101], v[184:187], v[214:217], v[98:101]
	v_mfma_f32_16x16x32_bf16 v[90:93], v[192:195], v[214:217], v[90:93]
	v_mfma_f32_16x16x32_bf16 v[82:85], v[184:187], v[222:225], v[82:85]
	v_mfma_f32_16x16x32_bf16 v[74:77], v[192:195], v[222:225], v[74:77]
	v_mfma_f32_16x16x32_bf16 v[70:73], v[184:187], v[230:233], v[70:73]
	v_mfma_f32_16x16x32_bf16 v[66:69], v[192:195], v[230:233], v[66:69]
	s_barrier
	s_add_i32 s44, s52, s5
	s_mov_b32 m0, s44
	ds_read_b128 v[196:199], v183 offset:49152
	ds_read_b128 v[200:203], v183 offset:50176
	ds_read_b128 v[210:213], v183 offset:51200
	ds_read_b128 v[214:217], v183 offset:52224
	ds_read_b128 v[218:221], v183 offset:53248
	ds_read_b128 v[222:225], v183 offset:54272
	ds_read_b128 v[226:229], v183 offset:55296
	ds_read_b128 v[230:233], v183 offset:56320
	v_lshl_add_u64 v[154:155], v[154:155], 0, s[34:35]
	global_load_lds_dwordx4 v[154:155], off
	s_add_i32 m0, s44, 0x2000
	s_add_u32 s42, s42, 0x80080
	v_lshl_add_u64 v[154:155], v[156:157], 0, s[34:35]
	s_addc_u32 s43, s43, 0
	s_add_i32 s44, s53, s5
	global_load_lds_dwordx4 v[154:155], off
	s_mov_b32 m0, s44
	s_nop 0
	global_load_lds_dwordx4 v162, s[42:43]
	s_add_i32 m0, s44, 0x2000
	s_nop 0
	global_load_lds_dwordx4 v158, s[42:43]
	v_lshl_add_u64 v[154:155], v[176:177], 0, s[34:35]
	s_mov_b32 m0, s19
	s_nop 0
	global_load_lds_dwordx4 v[154:155], off
	v_lshl_add_u64 v[154:155], v[180:181], 0, s[34:35]
	s_mov_b32 m0, s25
	s_nop 0
	global_load_lds_dwordx4 v[154:155], off
	s_waitcnt vmcnt(8) lgkmcnt(0)
	s_barrier
	v_mfma_f32_16x16x32_bf16 v[62:65], v[130:133], v[196:199], v[62:65]
	v_mfma_f32_16x16x32_bf16 v[58:61], v[138:141], v[196:199], v[58:61]
	v_mfma_f32_16x16x32_bf16 v[54:57], v[130:133], v[210:213], v[54:57]
	v_mfma_f32_16x16x32_bf16 v[46:49], v[138:141], v[210:213], v[46:49]
	v_mfma_f32_16x16x32_bf16 v[38:41], v[130:133], v[218:221], v[38:41]
	v_mfma_f32_16x16x32_bf16 v[30:33], v[138:141], v[218:221], v[30:33]
	v_mfma_f32_16x16x32_bf16 v[22:25], v[130:133], v[226:229], v[22:25]
	v_mfma_f32_16x16x32_bf16 v[14:17], v[138:141], v[226:229], v[14:17]
	v_mfma_f32_16x16x32_bf16 v[62:65], v[134:137], v[200:203], v[62:65]
	v_mfma_f32_16x16x32_bf16 v[58:61], v[142:145], v[200:203], v[58:61]
	v_mfma_f32_16x16x32_bf16 v[54:57], v[134:137], v[214:217], v[54:57]
	v_mfma_f32_16x16x32_bf16 v[46:49], v[142:145], v[214:217], v[46:49]
	v_mfma_f32_16x16x32_bf16 v[38:41], v[134:137], v[222:225], v[38:41]
	v_mfma_f32_16x16x32_bf16 v[30:33], v[142:145], v[222:225], v[30:33]
	v_mfma_f32_16x16x32_bf16 v[22:25], v[134:137], v[230:233], v[22:25]
	v_mfma_f32_16x16x32_bf16 v[14:17], v[142:145], v[230:233], v[14:17]
	v_mfma_f32_16x16x32_bf16 v[50:53], v[170:173], v[196:199], v[50:53]
	v_mfma_f32_16x16x32_bf16 v[42:45], v[188:191], v[196:199], v[42:45]
	v_mfma_f32_16x16x32_bf16 v[34:37], v[170:173], v[210:213], v[34:37]
	v_mfma_f32_16x16x32_bf16 v[26:29], v[188:191], v[210:213], v[26:29]
	v_mfma_f32_16x16x32_bf16 v[18:21], v[170:173], v[218:221], v[18:21]
	v_mfma_f32_16x16x32_bf16 v[10:13], v[188:191], v[218:221], v[10:13]
	v_mfma_f32_16x16x32_bf16 v[6:9], v[170:173], v[226:229], v[6:9]
	v_mfma_f32_16x16x32_bf16 v[2:5], v[188:191], v[226:229], v[2:5]
	v_mfma_f32_16x16x32_bf16 v[50:53], v[184:187], v[200:203], v[50:53]
	v_mfma_f32_16x16x32_bf16 v[42:45], v[192:195], v[200:203], v[42:45]
	v_mfma_f32_16x16x32_bf16 v[34:37], v[184:187], v[214:217], v[34:37]
	v_mfma_f32_16x16x32_bf16 v[26:29], v[192:195], v[214:217], v[26:29]
	v_mfma_f32_16x16x32_bf16 v[18:21], v[184:187], v[222:225], v[18:21]
	v_mfma_f32_16x16x32_bf16 v[10:13], v[192:195], v[222:225], v[10:13]
	v_mfma_f32_16x16x32_bf16 v[6:9], v[184:187], v[230:233], v[6:9]
	v_mfma_f32_16x16x32_bf16 v[2:5], v[192:195], v[230:233], v[2:5]
	s_barrier
	s_add_i32 s51, s51, 2
	s_add_u32 s40, s40, 0x100
	s_addc_u32 s41, s41, 0
	s_add_u32 s49, s49, 0x100
	s_addc_u32 s50, s50, 0
	s_cmp_gt_u32 s51, 29
	s_cbranch_scc0 .LBB0_169
	s_setprio 0
	s_and_b64 vcc, exec, s[8:9]
	s_cbranch_vccz .LBB0_172
	s_barrier

.LBB0_516:
	s_add_u32 s46, s44, 0xfff80080
	s_addc_u32 s47, s45, -1
	s_add_i32 s58, 0, 0x10000
	s_cmp_eq_u32 s57, 28
	s_cselect_b32 s49, s21, s47
	s_cselect_b32 s48, s50, s46
	s_cselect_b32 s47, s13, s56
	s_cselect_b32 s46, s51, s55
	s_add_i32 s60, 0, 0x14000
	ds_read_b128 v[82:85], v236
	ds_read_b128 v[86:89], v236 offset:1024
	ds_read_b128 v[98:101], v236 offset:2048
	ds_read_b128 v[102:105], v236 offset:3072
	ds_read_b128 v[154:157], v237
	ds_read_b128 v[168:171], v237 offset:1024
	ds_read_b128 v[176:179], v237 offset:2048
	ds_read_b128 v[180:183], v237 offset:3072
	s_add_i32 m0, s14, 0xc000
	ds_read_b128 v[184:187], v174
	ds_read_b128 v[188:191], v174 offset:1024
	ds_read_b128 v[192:195], v174 offset:2048
	ds_read_b128 v[196:199], v174 offset:3072
	ds_read_b128 v[200:203], v174 offset:4096
	ds_read_b128 v[210:213], v174 offset:5120
	ds_read_b128 v[214:217], v174 offset:6144
	ds_read_b128 v[218:221], v174 offset:7168
	global_load_lds_dwordx4 v164, s[44:45]
	s_add_i32 m0, s14, 0xe000
	s_nop 0
	global_load_lds_dwordx4 v166, s[44:45]
	s_waitcnt vmcnt(8) lgkmcnt(0)
	s_barrier
	v_mfma_f32_16x16x32_bf16 v[142:145], v[82:85], v[184:187], v[142:145]
	v_mfma_f32_16x16x32_bf16 v[138:141], v[98:101], v[184:187], v[138:141]
	v_mfma_f32_16x16x32_bf16 v[126:129], v[82:85], v[192:195], v[126:129]
	v_mfma_f32_16x16x32_bf16 v[122:125], v[98:101], v[192:195], v[122:125]
	v_mfma_f32_16x16x32_bf16 v[110:113], v[82:85], v[200:203], v[110:113]
	v_mfma_f32_16x16x32_bf16 v[106:109], v[98:101], v[200:203], v[106:109]
	v_mfma_f32_16x16x32_bf16 v[78:81], v[82:85], v[214:217], v[78:81]
	v_mfma_f32_16x16x32_bf16 v[74:77], v[98:101], v[214:217], v[74:77]
	v_mfma_f32_16x16x32_bf16 v[142:145], v[86:89], v[188:191], v[142:145]
	v_mfma_f32_16x16x32_bf16 v[138:141], v[102:105], v[188:191], v[138:141]
	v_mfma_f32_16x16x32_bf16 v[126:129], v[86:89], v[196:199], v[126:129]
	v_mfma_f32_16x16x32_bf16 v[122:125], v[102:105], v[196:199], v[122:125]
	v_mfma_f32_16x16x32_bf16 v[110:113], v[86:89], v[210:213], v[110:113]
	v_mfma_f32_16x16x32_bf16 v[106:109], v[102:105], v[210:213], v[106:109]
	v_mfma_f32_16x16x32_bf16 v[78:81], v[86:89], v[218:221], v[78:81]
	v_mfma_f32_16x16x32_bf16 v[74:77], v[102:105], v[218:221], v[74:77]
	v_mfma_f32_16x16x32_bf16 v[134:137], v[154:157], v[184:187], v[134:137]
	v_mfma_f32_16x16x32_bf16 v[130:133], v[176:179], v[184:187], v[130:133]
	v_mfma_f32_16x16x32_bf16 v[118:121], v[154:157], v[192:195], v[118:121]
	v_mfma_f32_16x16x32_bf16 v[114:117], v[176:179], v[192:195], v[114:117]
	v_mfma_f32_16x16x32_bf16 v[94:97], v[154:157], v[200:203], v[94:97]
	v_mfma_f32_16x16x32_bf16 v[90:93], v[176:179], v[200:203], v[90:93]
	v_mfma_f32_16x16x32_bf16 v[70:73], v[154:157], v[214:217], v[70:73]
	v_mfma_f32_16x16x32_bf16 v[66:69], v[176:179], v[214:217], v[66:69]
	v_mfma_f32_16x16x32_bf16 v[134:137], v[168:171], v[188:191], v[134:137]
	v_mfma_f32_16x16x32_bf16 v[130:133], v[180:183], v[188:191], v[130:133]
	v_mfma_f32_16x16x32_bf16 v[118:121], v[168:171], v[196:199], v[118:121]
	v_mfma_f32_16x16x32_bf16 v[114:117], v[180:183], v[196:199], v[114:117]
	v_mfma_f32_16x16x32_bf16 v[94:97], v[168:171], v[210:213], v[94:97]
	v_mfma_f32_16x16x32_bf16 v[90:93], v[180:183], v[210:213], v[90:93]
	v_mfma_f32_16x16x32_bf16 v[70:73], v[168:171], v[218:221], v[70:73]
	v_mfma_f32_16x16x32_bf16 v[66:69], v[180:183], v[218:221], v[66:69]
	s_barrier
	s_add_i32 s58, s58, s5
	s_mov_b32 m0, s58
	ds_read_b128 v[184:187], v174 offset:16384
	ds_read_b128 v[188:191], v174 offset:17408
	ds_read_b128 v[192:195], v174 offset:18432
	ds_read_b128 v[196:199], v174 offset:19456
	ds_read_b128 v[200:203], v174 offset:20480
	ds_read_b128 v[210:213], v174 offset:21504
	ds_read_b128 v[214:217], v174 offset:22528
	ds_read_b128 v[218:221], v174 offset:23552
	v_lshl_add_u64 v[222:223], s[46:47], 0, v[0:1]
	global_load_lds_dwordx4 v[222:223], off
	s_add_i32 m0, s58, 0x2000
	s_add_u32 s58, s46, 0x80000
	v_lshl_add_u64 v[224:225], s[46:47], 0, v[158:159]
	s_addc_u32 s59, s47, 0
	s_add_i32 s60, s60, s5
	global_load_lds_dwordx4 v[224:225], off
	s_mov_b32 m0, s60
	v_lshl_add_u64 v[228:229], s[48:49], 0, v[160:161]
	global_load_lds_dwordx4 v0, s[58:59]
	s_add_i32 m0, s60, 0x2000
	s_nop 0
	global_load_lds_dwordx4 v158, s[58:59]
	v_lshl_add_u64 v[226:227], s[48:49], 0, v[162:163]
	s_mov_b32 m0, s14
	s_nop 0
	global_load_lds_dwordx4 v[226:227], off
	s_mov_b32 m0, s15
	s_nop 0
	global_load_lds_dwordx4 v[228:229], off
	s_waitcnt vmcnt(8) lgkmcnt(0)
	s_barrier
	v_mfma_f32_16x16x32_bf16 v[62:65], v[82:85], v[184:187], v[62:65]
	v_mfma_f32_16x16x32_bf16 v[58:61], v[98:101], v[184:187], v[58:61]
	v_mfma_f32_16x16x32_bf16 v[46:49], v[82:85], v[192:195], v[46:49]
	v_mfma_f32_16x16x32_bf16 v[42:45], v[98:101], v[192:195], v[42:45]
	v_mfma_f32_16x16x32_bf16 v[30:33], v[82:85], v[200:203], v[30:33]
	v_mfma_f32_16x16x32_bf16 v[26:29], v[98:101], v[200:203], v[26:29]
	v_mfma_f32_16x16x32_bf16 v[14:17], v[82:85], v[214:217], v[14:17]
	v_mfma_f32_16x16x32_bf16 v[10:13], v[98:101], v[214:217], v[10:13]
	v_mfma_f32_16x16x32_bf16 v[62:65], v[86:89], v[188:191], v[62:65]
	v_mfma_f32_16x16x32_bf16 v[58:61], v[102:105], v[188:191], v[58:61]
	v_mfma_f32_16x16x32_bf16 v[46:49], v[86:89], v[196:199], v[46:49]
	v_mfma_f32_16x16x32_bf16 v[42:45], v[102:105], v[196:199], v[42:45]
	v_mfma_f32_16x16x32_bf16 v[30:33], v[86:89], v[210:213], v[30:33]
	v_mfma_f32_16x16x32_bf16 v[26:29], v[102:105], v[210:213], v[26:29]
	v_mfma_f32_16x16x32_bf16 v[14:17], v[86:89], v[218:221], v[14:17]
	v_mfma_f32_16x16x32_bf16 v[10:13], v[102:105], v[218:221], v[10:13]
	v_mfma_f32_16x16x32_bf16 v[54:57], v[154:157], v[184:187], v[54:57]
	v_mfma_f32_16x16x32_bf16 v[50:53], v[176:179], v[184:187], v[50:53]
	v_mfma_f32_16x16x32_bf16 v[38:41], v[154:157], v[192:195], v[38:41]
	v_mfma_f32_16x16x32_bf16 v[34:37], v[176:179], v[192:195], v[34:37]
	v_mfma_f32_16x16x32_bf16 v[22:25], v[154:157], v[200:203], v[22:25]
	v_mfma_f32_16x16x32_bf16 v[18:21], v[176:179], v[200:203], v[18:21]
	v_mfma_f32_16x16x32_bf16 v[6:9], v[154:157], v[214:217], v[6:9]
	v_mfma_f32_16x16x32_bf16 v[2:5], v[176:179], v[214:217], v[2:5]
	v_mfma_f32_16x16x32_bf16 v[54:57], v[168:171], v[188:191], v[54:57]
	v_mfma_f32_16x16x32_bf16 v[50:53], v[180:183], v[188:191], v[50:53]
	v_mfma_f32_16x16x32_bf16 v[38:41], v[168:171], v[196:199], v[38:41]
	v_mfma_f32_16x16x32_bf16 v[34:37], v[180:183], v[196:199], v[34:37]
	v_mfma_f32_16x16x32_bf16 v[22:25], v[168:171], v[210:213], v[22:25]
	v_mfma_f32_16x16x32_bf16 v[18:21], v[180:183], v[210:213], v[18:21]
	v_mfma_f32_16x16x32_bf16 v[6:9], v[168:171], v[218:221], v[6:9]
	v_mfma_f32_16x16x32_bf16 v[2:5], v[180:183], v[218:221], v[2:5]
	s_barrier
	s_add_i32 s58, 0, 0x18000
	s_add_i32 s59, 0, 0x1c000
	ds_read_b128 v[82:85], v238
	ds_read_b128 v[86:89], v238 offset:1024
	ds_read_b128 v[98:101], v238 offset:2048
	ds_read_b128 v[102:105], v238 offset:3072
	ds_read_b128 v[154:157], v239
	ds_read_b128 v[168:171], v239 offset:1024
	ds_read_b128 v[176:179], v239 offset:2048
	ds_read_b128 v[180:183], v239 offset:3072
	s_add_u32 s48, s48, 0x80000
	s_addc_u32 s49, s49, 0
	s_mov_b32 m0, s16
	ds_read_b128 v[184:187], v174 offset:32768
	ds_read_b128 v[188:191], v174 offset:33792
	ds_read_b128 v[192:195], v174 offset:34816
	ds_read_b128 v[196:199], v174 offset:35840
	ds_read_b128 v[200:203], v174 offset:36864
	ds_read_b128 v[210:213], v174 offset:37888
	ds_read_b128 v[214:217], v174 offset:38912
	ds_read_b128 v[218:221], v174 offset:39936
	global_load_lds_dwordx4 v162, s[48:49]
	s_mov_b32 m0, s18
	s_nop 0
	global_load_lds_dwordx4 v160, s[48:49]
	s_waitcnt vmcnt(8) lgkmcnt(0)
	s_barrier
	v_mfma_f32_16x16x32_bf16 v[142:145], v[82:85], v[184:187], v[142:145]
	v_mfma_f32_16x16x32_bf16 v[138:141], v[98:101], v[184:187], v[138:141]
	v_mfma_f32_16x16x32_bf16 v[126:129], v[82:85], v[192:195], v[126:129]
	v_mfma_f32_16x16x32_bf16 v[122:125], v[98:101], v[192:195], v[122:125]
	v_mfma_f32_16x16x32_bf16 v[110:113], v[82:85], v[200:203], v[110:113]
	v_mfma_f32_16x16x32_bf16 v[106:109], v[98:101], v[200:203], v[106:109]
	v_mfma_f32_16x16x32_bf16 v[78:81], v[82:85], v[214:217], v[78:81]
	v_mfma_f32_16x16x32_bf16 v[74:77], v[98:101], v[214:217], v[74:77]
	v_mfma_f32_16x16x32_bf16 v[142:145], v[86:89], v[188:191], v[142:145]
	v_mfma_f32_16x16x32_bf16 v[138:141], v[102:105], v[188:191], v[138:141]
	v_mfma_f32_16x16x32_bf16 v[126:129], v[86:89], v[196:199], v[126:129]
	v_mfma_f32_16x16x32_bf16 v[122:125], v[102:105], v[196:199], v[122:125]
	v_mfma_f32_16x16x32_bf16 v[110:113], v[86:89], v[210:213], v[110:113]
	v_mfma_f32_16x16x32_bf16 v[106:109], v[102:105], v[210:213], v[106:109]
	v_mfma_f32_16x16x32_bf16 v[78:81], v[86:89], v[218:221], v[78:81]
	v_mfma_f32_16x16x32_bf16 v[74:77], v[102:105], v[218:221], v[74:77]
	v_mfma_f32_16x16x32_bf16 v[134:137], v[154:157], v[184:187], v[134:137]
	v_mfma_f32_16x16x32_bf16 v[130:133], v[176:179], v[184:187], v[130:133]
	v_mfma_f32_16x16x32_bf16 v[118:121], v[154:157], v[192:195], v[118:121]
	v_mfma_f32_16x16x32_bf16 v[114:117], v[176:179], v[192:195], v[114:117]
	v_mfma_f32_16x16x32_bf16 v[94:97], v[154:157], v[200:203], v[94:97]
	v_mfma_f32_16x16x32_bf16 v[90:93], v[176:179], v[200:203], v[90:93]
	v_mfma_f32_16x16x32_bf16 v[70:73], v[154:157], v[214:217], v[70:73]
	v_mfma_f32_16x16x32_bf16 v[66:69], v[176:179], v[214:217], v[66:69]
	v_mfma_f32_16x16x32_bf16 v[134:137], v[168:171], v[188:191], v[134:137]
	v_mfma_f32_16x16x32_bf16 v[130:133], v[180:183], v[188:191], v[130:133]
	v_mfma_f32_16x16x32_bf16 v[118:121], v[168:171], v[196:199], v[118:121]
	v_mfma_f32_16x16x32_bf16 v[114:117], v[180:183], v[196:199], v[114:117]
	v_mfma_f32_16x16x32_bf16 v[94:97], v[168:171], v[210:213], v[94:97]
	v_mfma_f32_16x16x32_bf16 v[90:93], v[180:183], v[210:213], v[90:93]
	v_mfma_f32_16x16x32_bf16 v[70:73], v[168:171], v[218:221], v[70:73]
	v_mfma_f32_16x16x32_bf16 v[66:69], v[180:183], v[218:221], v[66:69]
	s_barrier
	s_add_i32 s48, s58, s5
	s_mov_b32 m0, s48
	ds_read_b128 v[184:187], v174 offset:49152
	ds_read_b128 v[188:191], v174 offset:50176
	ds_read_b128 v[192:195], v174 offset:51200
	ds_read_b128 v[196:199], v174 offset:52224
	ds_read_b128 v[200:203], v174 offset:53248
	ds_read_b128 v[210:213], v174 offset:54272
	ds_read_b128 v[214:217], v174 offset:55296
	ds_read_b128 v[218:221], v174 offset:56320
	v_lshl_add_u64 v[222:223], v[222:223], 0, s[34:35]
	global_load_lds_dwordx4 v[222:223], off
	s_add_i32 m0, s48, 0x2000
	s_add_u32 s46, s46, 0x80080
	v_lshl_add_u64 v[222:223], v[224:225], 0, s[34:35]
	s_addc_u32 s47, s47, 0
	s_add_i32 s48, s59, s5
	global_load_lds_dwordx4 v[222:223], off
	s_mov_b32 m0, s48
	s_nop 0
	global_load_lds_dwordx4 v0, s[46:47]
	s_add_i32 m0, s48, 0x2000
	s_nop 0
	global_load_lds_dwordx4 v158, s[46:47]
	v_lshl_add_u64 v[222:223], v[226:227], 0, s[34:35]
	s_mov_b32 m0, s25
	s_nop 0
	global_load_lds_dwordx4 v[222:223], off
	v_lshl_add_u64 v[222:223], v[228:229], 0, s[34:35]
	s_mov_b32 m0, s33
	s_nop 0
	global_load_lds_dwordx4 v[222:223], off
	s_waitcnt vmcnt(8) lgkmcnt(0)
	s_barrier
	v_mfma_f32_16x16x32_bf16 v[62:65], v[82:85], v[184:187], v[62:65]
	v_mfma_f32_16x16x32_bf16 v[58:61], v[98:101], v[184:187], v[58:61]
	v_mfma_f32_16x16x32_bf16 v[46:49], v[82:85], v[192:195], v[46:49]
	v_mfma_f32_16x16x32_bf16 v[42:45], v[98:101], v[192:195], v[42:45]
	v_mfma_f32_16x16x32_bf16 v[30:33], v[82:85], v[200:203], v[30:33]
	v_mfma_f32_16x16x32_bf16 v[26:29], v[98:101], v[200:203], v[26:29]
	v_mfma_f32_16x16x32_bf16 v[14:17], v[82:85], v[214:217], v[14:17]
	v_mfma_f32_16x16x32_bf16 v[10:13], v[98:101], v[214:217], v[10:13]
	v_mfma_f32_16x16x32_bf16 v[62:65], v[86:89], v[188:191], v[62:65]
	v_mfma_f32_16x16x32_bf16 v[58:61], v[102:105], v[188:191], v[58:61]
	v_mfma_f32_16x16x32_bf16 v[46:49], v[86:89], v[196:199], v[46:49]
	v_mfma_f32_16x16x32_bf16 v[42:45], v[102:105], v[196:199], v[42:45]
	v_mfma_f32_16x16x32_bf16 v[30:33], v[86:89], v[210:213], v[30:33]
	v_mfma_f32_16x16x32_bf16 v[26:29], v[102:105], v[210:213], v[26:29]
	v_mfma_f32_16x16x32_bf16 v[14:17], v[86:89], v[218:221], v[14:17]
	v_mfma_f32_16x16x32_bf16 v[10:13], v[102:105], v[218:221], v[10:13]
	v_mfma_f32_16x16x32_bf16 v[54:57], v[154:157], v[184:187], v[54:57]
	v_mfma_f32_16x16x32_bf16 v[50:53], v[176:179], v[184:187], v[50:53]
	v_mfma_f32_16x16x32_bf16 v[38:41], v[154:157], v[192:195], v[38:41]
	v_mfma_f32_16x16x32_bf16 v[34:37], v[176:179], v[192:195], v[34:37]
	v_mfma_f32_16x16x32_bf16 v[22:25], v[154:157], v[200:203], v[22:25]
	v_mfma_f32_16x16x32_bf16 v[18:21], v[176:179], v[200:203], v[18:21]
	v_mfma_f32_16x16x32_bf16 v[6:9], v[154:157], v[214:217], v[6:9]
	v_mfma_f32_16x16x32_bf16 v[2:5], v[176:179], v[214:217], v[2:5]
	v_mfma_f32_16x16x32_bf16 v[54:57], v[168:171], v[188:191], v[54:57]
	v_mfma_f32_16x16x32_bf16 v[50:53], v[180:183], v[188:191], v[50:53]
	v_mfma_f32_16x16x32_bf16 v[38:41], v[168:171], v[196:199], v[38:41]
	v_mfma_f32_16x16x32_bf16 v[34:37], v[180:183], v[196:199], v[34:37]
	v_mfma_f32_16x16x32_bf16 v[22:25], v[168:171], v[210:213], v[22:25]
	v_mfma_f32_16x16x32_bf16 v[18:21], v[180:183], v[210:213], v[18:21]
	v_mfma_f32_16x16x32_bf16 v[6:9], v[168:171], v[218:221], v[6:9]
	v_mfma_f32_16x16x32_bf16 v[2:5], v[180:183], v[218:221], v[2:5]
	s_barrier
	s_add_i32 s57, s57, 2
	s_add_u32 s44, s44, 0x100
	s_addc_u32 s45, s45, 0
	s_add_u32 s55, s55, 0x100
	s_addc_u32 s56, s56, 0
	s_cmp_gt_u32 s57, 29
	s_cbranch_scc0 .LBB0_516
	s_setprio 0
	s_and_b64 vcc, exec, s[10:11]
	s_cbranch_vccz .LBB0_519
	s_barrier

.LBB0_604:
	s_add_u32 s22, s6, 0xfff80080
	s_addc_u32 s23, s7, -1
	s_add_i32 s54, 0, 0x10000
	s_cmp_eq_u32 s53, 28
	s_cselect_b32 s47, s18, s23
	s_cselect_b32 s46, s19, s22
	s_cselect_b32 s23, s21, s52
	s_cselect_b32 s22, s25, s41
	s_add_i32 s56, 0, 0x14000
	ds_read_b128 v[130:133], v236
	ds_read_b128 v[134:137], v236 offset:1024
	ds_read_b128 v[154:157], v236 offset:2048
	ds_read_b128 v[162:165], v236 offset:3072
	ds_read_b128 v[166:169], v237
	ds_read_b128 v[170:173], v237 offset:1024
	ds_read_b128 v[180:183], v237 offset:2048
	ds_read_b128 v[184:187], v237 offset:3072
	s_add_i32 m0, s16, 0xc000
	ds_read_b128 v[188:191], v179
	ds_read_b128 v[192:195], v179 offset:1024
	ds_read_b128 v[196:199], v179 offset:2048
	ds_read_b128 v[200:203], v179 offset:3072
	ds_read_b128 v[210:213], v179 offset:4096
	ds_read_b128 v[214:217], v179 offset:5120
	ds_read_b128 v[218:221], v179 offset:6144
	ds_read_b128 v[222:225], v179 offset:7168
	global_load_lds_dwordx4 v158, s[6:7]
	s_add_i32 m0, s16, 0xe000
	s_nop 0
	global_load_lds_dwordx4 v160, s[6:7]
	s_waitcnt vmcnt(8) lgkmcnt(0)
	s_barrier
	v_mfma_f32_16x16x32_bf16 v[126:129], v[130:133], v[188:191], v[126:129]
	v_mfma_f32_16x16x32_bf16 v[122:125], v[154:157], v[188:191], v[122:125]
	v_mfma_f32_16x16x32_bf16 v[110:113], v[130:133], v[196:199], v[110:113]
	v_mfma_f32_16x16x32_bf16 v[106:109], v[154:157], v[196:199], v[106:109]
	v_mfma_f32_16x16x32_bf16 v[94:97], v[130:133], v[210:213], v[94:97]
	v_mfma_f32_16x16x32_bf16 v[90:93], v[154:157], v[210:213], v[90:93]
	v_mfma_f32_16x16x32_bf16 v[78:81], v[130:133], v[218:221], v[78:81]
	v_mfma_f32_16x16x32_bf16 v[74:77], v[154:157], v[218:221], v[74:77]
	v_mfma_f32_16x16x32_bf16 v[126:129], v[134:137], v[192:195], v[126:129]
	v_mfma_f32_16x16x32_bf16 v[122:125], v[162:165], v[192:195], v[122:125]
	v_mfma_f32_16x16x32_bf16 v[110:113], v[134:137], v[200:203], v[110:113]
	v_mfma_f32_16x16x32_bf16 v[106:109], v[162:165], v[200:203], v[106:109]
	v_mfma_f32_16x16x32_bf16 v[94:97], v[134:137], v[214:217], v[94:97]
	v_mfma_f32_16x16x32_bf16 v[90:93], v[162:165], v[214:217], v[90:93]
	v_mfma_f32_16x16x32_bf16 v[78:81], v[134:137], v[222:225], v[78:81]
	v_mfma_f32_16x16x32_bf16 v[74:77], v[162:165], v[222:225], v[74:77]
	v_mfma_f32_16x16x32_bf16 v[118:121], v[166:169], v[188:191], v[118:121]
	v_mfma_f32_16x16x32_bf16 v[114:117], v[180:183], v[188:191], v[114:117]
	v_mfma_f32_16x16x32_bf16 v[102:105], v[166:169], v[196:199], v[102:105]
	v_mfma_f32_16x16x32_bf16 v[98:101], v[180:183], v[196:199], v[98:101]
	v_mfma_f32_16x16x32_bf16 v[86:89], v[166:169], v[210:213], v[86:89]
	v_mfma_f32_16x16x32_bf16 v[82:85], v[180:183], v[210:213], v[82:85]
	v_mfma_f32_16x16x32_bf16 v[70:73], v[166:169], v[218:221], v[70:73]
	v_mfma_f32_16x16x32_bf16 v[66:69], v[180:183], v[218:221], v[66:69]
	v_mfma_f32_16x16x32_bf16 v[118:121], v[170:173], v[192:195], v[118:121]
	v_mfma_f32_16x16x32_bf16 v[114:117], v[184:187], v[192:195], v[114:117]
	v_mfma_f32_16x16x32_bf16 v[102:105], v[170:173], v[200:203], v[102:105]
	v_mfma_f32_16x16x32_bf16 v[98:101], v[184:187], v[200:203], v[98:101]
	v_mfma_f32_16x16x32_bf16 v[86:89], v[170:173], v[214:217], v[86:89]
	v_mfma_f32_16x16x32_bf16 v[82:85], v[184:187], v[214:217], v[82:85]
	v_mfma_f32_16x16x32_bf16 v[70:73], v[170:173], v[222:225], v[70:73]
	v_mfma_f32_16x16x32_bf16 v[66:69], v[184:187], v[222:225], v[66:69]
	s_barrier
	s_add_i32 s54, s54, s15
	s_mov_b32 m0, s54
	ds_read_b128 v[188:191], v179 offset:16384
	ds_read_b128 v[192:195], v179 offset:17408
	ds_read_b128 v[196:199], v179 offset:18432
	ds_read_b128 v[200:203], v179 offset:19456
	ds_read_b128 v[210:213], v179 offset:20480
	ds_read_b128 v[214:217], v179 offset:21504
	ds_read_b128 v[218:221], v179 offset:22528
	ds_read_b128 v[222:225], v179 offset:23552
	v_lshl_add_u64 v[226:227], s[22:23], 0, v[142:143]
	global_load_lds_dwordx4 v[226:227], off
	s_add_i32 m0, s54, 0x2000
	s_add_u32 s54, s22, 0x80000
	v_lshl_add_u64 v[228:229], s[22:23], 0, v[138:139]
	s_addc_u32 s55, s23, 0
	s_add_i32 s56, s56, s15
	global_load_lds_dwordx4 v[228:229], off
	s_mov_b32 m0, s56
	v_lshl_add_u64 v[232:233], s[46:47], 0, v[140:141]
	global_load_lds_dwordx4 v142, s[54:55]
	s_add_i32 m0, s56, 0x2000
	s_nop 0
	global_load_lds_dwordx4 v138, s[54:55]
	v_lshl_add_u64 v[230:231], s[46:47], 0, v[144:145]
	s_mov_b32 m0, s16
	s_nop 0
	global_load_lds_dwordx4 v[230:231], off
	s_mov_b32 m0, s33
	s_nop 0
	global_load_lds_dwordx4 v[232:233], off
	s_waitcnt vmcnt(8) lgkmcnt(0)
	s_barrier
	v_mfma_f32_16x16x32_bf16 v[62:65], v[130:133], v[188:191], v[62:65]
	v_mfma_f32_16x16x32_bf16 v[58:61], v[154:157], v[188:191], v[58:61]
	v_mfma_f32_16x16x32_bf16 v[46:49], v[130:133], v[196:199], v[46:49]
	v_mfma_f32_16x16x32_bf16 v[42:45], v[154:157], v[196:199], v[42:45]
	v_mfma_f32_16x16x32_bf16 v[30:33], v[130:133], v[210:213], v[30:33]
	v_mfma_f32_16x16x32_bf16 v[26:29], v[154:157], v[210:213], v[26:29]
	v_mfma_f32_16x16x32_bf16 v[14:17], v[130:133], v[218:221], v[14:17]
	v_mfma_f32_16x16x32_bf16 v[10:13], v[154:157], v[218:221], v[10:13]
	v_mfma_f32_16x16x32_bf16 v[62:65], v[134:137], v[192:195], v[62:65]
	v_mfma_f32_16x16x32_bf16 v[58:61], v[162:165], v[192:195], v[58:61]
	v_mfma_f32_16x16x32_bf16 v[46:49], v[134:137], v[200:203], v[46:49]
	v_mfma_f32_16x16x32_bf16 v[42:45], v[162:165], v[200:203], v[42:45]
	v_mfma_f32_16x16x32_bf16 v[30:33], v[134:137], v[214:217], v[30:33]
	v_mfma_f32_16x16x32_bf16 v[26:29], v[162:165], v[214:217], v[26:29]
	v_mfma_f32_16x16x32_bf16 v[14:17], v[134:137], v[222:225], v[14:17]
	v_mfma_f32_16x16x32_bf16 v[10:13], v[162:165], v[222:225], v[10:13]
	v_mfma_f32_16x16x32_bf16 v[54:57], v[166:169], v[188:191], v[54:57]
	v_mfma_f32_16x16x32_bf16 v[50:53], v[180:183], v[188:191], v[50:53]
	v_mfma_f32_16x16x32_bf16 v[38:41], v[166:169], v[196:199], v[38:41]
	v_mfma_f32_16x16x32_bf16 v[34:37], v[180:183], v[196:199], v[34:37]
	v_mfma_f32_16x16x32_bf16 v[22:25], v[166:169], v[210:213], v[22:25]
	v_mfma_f32_16x16x32_bf16 v[18:21], v[180:183], v[210:213], v[18:21]
	v_mfma_f32_16x16x32_bf16 v[6:9], v[166:169], v[218:221], v[6:9]
	v_mfma_f32_16x16x32_bf16 v[2:5], v[180:183], v[218:221], v[2:5]
	v_mfma_f32_16x16x32_bf16 v[54:57], v[170:173], v[192:195], v[54:57]
	v_mfma_f32_16x16x32_bf16 v[50:53], v[184:187], v[192:195], v[50:53]
	v_mfma_f32_16x16x32_bf16 v[38:41], v[170:173], v[200:203], v[38:41]
	v_mfma_f32_16x16x32_bf16 v[34:37], v[184:187], v[200:203], v[34:37]
	v_mfma_f32_16x16x32_bf16 v[22:25], v[170:173], v[214:217], v[22:25]
	v_mfma_f32_16x16x32_bf16 v[18:21], v[184:187], v[214:217], v[18:21]
	v_mfma_f32_16x16x32_bf16 v[6:9], v[170:173], v[222:225], v[6:9]
	v_mfma_f32_16x16x32_bf16 v[2:5], v[184:187], v[222:225], v[2:5]
	s_barrier
	s_add_i32 s54, 0, 0x18000
	s_add_i32 s55, 0, 0x1c000
	ds_read_b128 v[130:133], v238
	ds_read_b128 v[134:137], v238 offset:1024
	ds_read_b128 v[154:157], v238 offset:2048
	ds_read_b128 v[162:165], v238 offset:3072
	ds_read_b128 v[166:169], v239
	ds_read_b128 v[170:173], v239 offset:1024
	ds_read_b128 v[180:183], v239 offset:2048
	ds_read_b128 v[184:187], v239 offset:3072
	s_add_u32 s46, s46, 0x80000
	s_addc_u32 s47, s47, 0
	s_mov_b32 m0, s37
	ds_read_b128 v[188:191], v179 offset:32768
	ds_read_b128 v[192:195], v179 offset:33792
	ds_read_b128 v[196:199], v179 offset:34816
	ds_read_b128 v[200:203], v179 offset:35840
	ds_read_b128 v[210:213], v179 offset:36864
	ds_read_b128 v[214:217], v179 offset:37888
	ds_read_b128 v[218:221], v179 offset:38912
	ds_read_b128 v[222:225], v179 offset:39936
	global_load_lds_dwordx4 v144, s[46:47]
	s_mov_b32 m0, s48
	s_nop 0
	global_load_lds_dwordx4 v140, s[46:47]
	s_waitcnt vmcnt(8) lgkmcnt(0)
	s_barrier
	v_mfma_f32_16x16x32_bf16 v[126:129], v[130:133], v[188:191], v[126:129]
	v_mfma_f32_16x16x32_bf16 v[122:125], v[154:157], v[188:191], v[122:125]
	v_mfma_f32_16x16x32_bf16 v[110:113], v[130:133], v[196:199], v[110:113]
	v_mfma_f32_16x16x32_bf16 v[106:109], v[154:157], v[196:199], v[106:109]
	v_mfma_f32_16x16x32_bf16 v[94:97], v[130:133], v[210:213], v[94:97]
	v_mfma_f32_16x16x32_bf16 v[90:93], v[154:157], v[210:213], v[90:93]
	v_mfma_f32_16x16x32_bf16 v[78:81], v[130:133], v[218:221], v[78:81]
	v_mfma_f32_16x16x32_bf16 v[74:77], v[154:157], v[218:221], v[74:77]
	v_mfma_f32_16x16x32_bf16 v[126:129], v[134:137], v[192:195], v[126:129]
	v_mfma_f32_16x16x32_bf16 v[122:125], v[162:165], v[192:195], v[122:125]
	v_mfma_f32_16x16x32_bf16 v[110:113], v[134:137], v[200:203], v[110:113]
	v_mfma_f32_16x16x32_bf16 v[106:109], v[162:165], v[200:203], v[106:109]
	v_mfma_f32_16x16x32_bf16 v[94:97], v[134:137], v[214:217], v[94:97]
	v_mfma_f32_16x16x32_bf16 v[90:93], v[162:165], v[214:217], v[90:93]
	v_mfma_f32_16x16x32_bf16 v[78:81], v[134:137], v[222:225], v[78:81]
	v_mfma_f32_16x16x32_bf16 v[74:77], v[162:165], v[222:225], v[74:77]
	v_mfma_f32_16x16x32_bf16 v[118:121], v[166:169], v[188:191], v[118:121]
	v_mfma_f32_16x16x32_bf16 v[114:117], v[180:183], v[188:191], v[114:117]
	v_mfma_f32_16x16x32_bf16 v[102:105], v[166:169], v[196:199], v[102:105]
	v_mfma_f32_16x16x32_bf16 v[98:101], v[180:183], v[196:199], v[98:101]
	v_mfma_f32_16x16x32_bf16 v[86:89], v[166:169], v[210:213], v[86:89]
	v_mfma_f32_16x16x32_bf16 v[82:85], v[180:183], v[210:213], v[82:85]
	v_mfma_f32_16x16x32_bf16 v[70:73], v[166:169], v[218:221], v[70:73]
	v_mfma_f32_16x16x32_bf16 v[66:69], v[180:183], v[218:221], v[66:69]
	v_mfma_f32_16x16x32_bf16 v[118:121], v[170:173], v[192:195], v[118:121]
	v_mfma_f32_16x16x32_bf16 v[114:117], v[184:187], v[192:195], v[114:117]
	v_mfma_f32_16x16x32_bf16 v[102:105], v[170:173], v[200:203], v[102:105]
	v_mfma_f32_16x16x32_bf16 v[98:101], v[184:187], v[200:203], v[98:101]
	v_mfma_f32_16x16x32_bf16 v[86:89], v[170:173], v[214:217], v[86:89]
	v_mfma_f32_16x16x32_bf16 v[82:85], v[184:187], v[214:217], v[82:85]
	v_mfma_f32_16x16x32_bf16 v[70:73], v[170:173], v[222:225], v[70:73]
	v_mfma_f32_16x16x32_bf16 v[66:69], v[184:187], v[222:225], v[66:69]
	s_barrier
	s_add_i32 s46, s54, s15
	s_mov_b32 m0, s46
	ds_read_b128 v[188:191], v179 offset:49152
	ds_read_b128 v[192:195], v179 offset:50176
	ds_read_b128 v[196:199], v179 offset:51200
	ds_read_b128 v[200:203], v179 offset:52224
	ds_read_b128 v[210:213], v179 offset:53248
	ds_read_b128 v[214:217], v179 offset:54272
	ds_read_b128 v[218:221], v179 offset:55296
	ds_read_b128 v[222:225], v179 offset:56320
	v_lshl_add_u64 v[226:227], v[226:227], 0, s[34:35]
	global_load_lds_dwordx4 v[226:227], off
	s_add_i32 m0, s46, 0x2000
	s_add_u32 s22, s22, 0x80080
	v_lshl_add_u64 v[226:227], v[228:229], 0, s[34:35]
	s_addc_u32 s23, s23, 0
	s_add_i32 s46, s55, s15
	global_load_lds_dwordx4 v[226:227], off
	s_mov_b32 m0, s46
	s_nop 0
	global_load_lds_dwordx4 v142, s[22:23]
	s_add_i32 m0, s46, 0x2000
	s_nop 0
	global_load_lds_dwordx4 v138, s[22:23]
	v_lshl_add_u64 v[226:227], v[230:231], 0, s[34:35]
	s_mov_b32 m0, s49
	s_nop 0
	global_load_lds_dwordx4 v[226:227], off
	v_lshl_add_u64 v[226:227], v[232:233], 0, s[34:35]
	s_mov_b32 m0, s50
	s_nop 0
	global_load_lds_dwordx4 v[226:227], off
	s_waitcnt vmcnt(8) lgkmcnt(0)
	s_barrier
	v_mfma_f32_16x16x32_bf16 v[62:65], v[130:133], v[188:191], v[62:65]
	v_mfma_f32_16x16x32_bf16 v[58:61], v[154:157], v[188:191], v[58:61]
	v_mfma_f32_16x16x32_bf16 v[46:49], v[130:133], v[196:199], v[46:49]
	v_mfma_f32_16x16x32_bf16 v[42:45], v[154:157], v[196:199], v[42:45]
	v_mfma_f32_16x16x32_bf16 v[30:33], v[130:133], v[210:213], v[30:33]
	v_mfma_f32_16x16x32_bf16 v[26:29], v[154:157], v[210:213], v[26:29]
	v_mfma_f32_16x16x32_bf16 v[14:17], v[130:133], v[218:221], v[14:17]
	v_mfma_f32_16x16x32_bf16 v[10:13], v[154:157], v[218:221], v[10:13]
	v_mfma_f32_16x16x32_bf16 v[62:65], v[134:137], v[192:195], v[62:65]
	v_mfma_f32_16x16x32_bf16 v[58:61], v[162:165], v[192:195], v[58:61]
	v_mfma_f32_16x16x32_bf16 v[46:49], v[134:137], v[200:203], v[46:49]
	v_mfma_f32_16x16x32_bf16 v[42:45], v[162:165], v[200:203], v[42:45]
	v_mfma_f32_16x16x32_bf16 v[30:33], v[134:137], v[214:217], v[30:33]
	v_mfma_f32_16x16x32_bf16 v[26:29], v[162:165], v[214:217], v[26:29]
	v_mfma_f32_16x16x32_bf16 v[14:17], v[134:137], v[222:225], v[14:17]
	v_mfma_f32_16x16x32_bf16 v[10:13], v[162:165], v[222:225], v[10:13]
	v_mfma_f32_16x16x32_bf16 v[54:57], v[166:169], v[188:191], v[54:57]
	v_mfma_f32_16x16x32_bf16 v[50:53], v[180:183], v[188:191], v[50:53]
	v_mfma_f32_16x16x32_bf16 v[38:41], v[166:169], v[196:199], v[38:41]
	v_mfma_f32_16x16x32_bf16 v[34:37], v[180:183], v[196:199], v[34:37]
	v_mfma_f32_16x16x32_bf16 v[22:25], v[166:169], v[210:213], v[22:25]
	v_mfma_f32_16x16x32_bf16 v[18:21], v[180:183], v[210:213], v[18:21]
	v_mfma_f32_16x16x32_bf16 v[6:9], v[166:169], v[218:221], v[6:9]
	v_mfma_f32_16x16x32_bf16 v[2:5], v[180:183], v[218:221], v[2:5]
	v_mfma_f32_16x16x32_bf16 v[54:57], v[170:173], v[192:195], v[54:57]
	v_mfma_f32_16x16x32_bf16 v[50:53], v[184:187], v[192:195], v[50:53]
	v_mfma_f32_16x16x32_bf16 v[38:41], v[170:173], v[200:203], v[38:41]
	v_mfma_f32_16x16x32_bf16 v[34:37], v[184:187], v[200:203], v[34:37]
	v_mfma_f32_16x16x32_bf16 v[22:25], v[170:173], v[214:217], v[22:25]
	v_mfma_f32_16x16x32_bf16 v[18:21], v[184:187], v[214:217], v[18:21]
	v_mfma_f32_16x16x32_bf16 v[6:9], v[170:173], v[222:225], v[6:9]
	v_mfma_f32_16x16x32_bf16 v[2:5], v[184:187], v[222:225], v[2:5]
	s_barrier
	s_add_i32 s53, s53, 2
	s_add_u32 s6, s6, 0x100
	s_addc_u32 s7, s7, 0
	s_add_u32 s41, s41, 0x100
	s_addc_u32 s52, s52, 0
	s_cmp_gt_u32 s53, 29
	s_cbranch_scc0 .LBB0_604
	s_setprio 0
	s_and_b64 vcc, exec, s[12:13]
	s_cbranch_vccz .LBB0_607
	s_barrier

.LBB0_728:
	s_add_u32 s42, s22, 0x100
	s_addc_u32 s43, s23, 0
	s_add_i32 s50, 0, 0x10000
	s_cmpk_eq_i32 s25, 0x54
	s_cselect_b32 s49, s21, s43
	s_cselect_b32 s48, s20, s42
	s_cselect_b32 s47, s45, s19
	s_cselect_b32 s46, s44, s18
	s_add_i32 s51, 0, 0x14000
	ds_read_b128 v[42:45], v236
	ds_read_b128 v[46:49], v236 offset:1024
	ds_read_b128 v[50:53], v236 offset:2048
	ds_read_b128 v[54:57], v236 offset:3072
	ds_read_b128 v[154:157], v237
	ds_read_b128 v[168:171], v237 offset:1024
	ds_read_b128 v[172:175], v237 offset:2048
	ds_read_b128 v[180:183], v237 offset:3072
	s_add_i32 m0, s33, 0xc000
	ds_read_b128 v[184:187], v178
	ds_read_b128 v[188:191], v178 offset:1024
	ds_read_b128 v[192:195], v178 offset:2048
	ds_read_b128 v[196:199], v178 offset:3072
	ds_read_b128 v[200:203], v178 offset:4096
	ds_read_b128 v[210:213], v178 offset:5120
	ds_read_b128 v[214:217], v178 offset:6144
	ds_read_b128 v[218:221], v178 offset:7168
	global_load_lds_dwordx4 v164, s[22:23]
	s_add_i32 m0, s33, 0xe000
	s_nop 0
	global_load_lds_dwordx4 v166, s[22:23]
	s_waitcnt vmcnt(8) lgkmcnt(0)
	s_barrier
	v_mfma_f32_16x16x32_bf16 v[142:145], v[42:45], v[184:187], v[142:145]
	v_mfma_f32_16x16x32_bf16 v[138:141], v[50:53], v[184:187], v[138:141]
	v_mfma_f32_16x16x32_bf16 v[126:129], v[42:45], v[192:195], v[126:129]
	v_mfma_f32_16x16x32_bf16 v[122:125], v[50:53], v[192:195], v[122:125]
	v_mfma_f32_16x16x32_bf16 v[110:113], v[42:45], v[200:203], v[110:113]
	v_mfma_f32_16x16x32_bf16 v[106:109], v[50:53], v[200:203], v[106:109]
	v_mfma_f32_16x16x32_bf16 v[94:97], v[42:45], v[214:217], v[94:97]
	v_mfma_f32_16x16x32_bf16 v[90:93], v[50:53], v[214:217], v[90:93]
	v_mfma_f32_16x16x32_bf16 v[142:145], v[46:49], v[188:191], v[142:145]
	v_mfma_f32_16x16x32_bf16 v[138:141], v[54:57], v[188:191], v[138:141]
	v_mfma_f32_16x16x32_bf16 v[126:129], v[46:49], v[196:199], v[126:129]
	v_mfma_f32_16x16x32_bf16 v[122:125], v[54:57], v[196:199], v[122:125]
	v_mfma_f32_16x16x32_bf16 v[110:113], v[46:49], v[210:213], v[110:113]
	v_mfma_f32_16x16x32_bf16 v[106:109], v[54:57], v[210:213], v[106:109]
	v_mfma_f32_16x16x32_bf16 v[94:97], v[46:49], v[218:221], v[94:97]
	v_mfma_f32_16x16x32_bf16 v[90:93], v[54:57], v[218:221], v[90:93]
	v_mfma_f32_16x16x32_bf16 v[134:137], v[154:157], v[184:187], v[134:137]
	v_mfma_f32_16x16x32_bf16 v[130:133], v[172:175], v[184:187], v[130:133]
	v_mfma_f32_16x16x32_bf16 v[118:121], v[154:157], v[192:195], v[118:121]
	v_mfma_f32_16x16x32_bf16 v[114:117], v[172:175], v[192:195], v[114:117]
	v_mfma_f32_16x16x32_bf16 v[102:105], v[154:157], v[200:203], v[102:105]
	v_mfma_f32_16x16x32_bf16 v[98:101], v[172:175], v[200:203], v[98:101]
	v_mfma_f32_16x16x32_bf16 v[86:89], v[154:157], v[214:217], v[86:89]
	v_mfma_f32_16x16x32_bf16 v[82:85], v[172:175], v[214:217], v[82:85]
	v_mfma_f32_16x16x32_bf16 v[134:137], v[168:171], v[188:191], v[134:137]
	v_mfma_f32_16x16x32_bf16 v[130:133], v[180:183], v[188:191], v[130:133]
	v_mfma_f32_16x16x32_bf16 v[118:121], v[168:171], v[196:199], v[118:121]
	v_mfma_f32_16x16x32_bf16 v[114:117], v[180:183], v[196:199], v[114:117]
	v_mfma_f32_16x16x32_bf16 v[102:105], v[168:171], v[210:213], v[102:105]
	v_mfma_f32_16x16x32_bf16 v[98:101], v[180:183], v[210:213], v[98:101]
	v_mfma_f32_16x16x32_bf16 v[86:89], v[168:171], v[218:221], v[86:89]
	v_mfma_f32_16x16x32_bf16 v[82:85], v[180:183], v[218:221], v[82:85]
	s_barrier
	s_add_i32 s22, s50, s16
	s_mov_b32 m0, s22
	ds_read_b128 v[184:187], v178 offset:16384
	ds_read_b128 v[188:191], v178 offset:17408
	ds_read_b128 v[192:195], v178 offset:18432
	ds_read_b128 v[196:199], v178 offset:19456
	ds_read_b128 v[200:203], v178 offset:20480
	ds_read_b128 v[210:213], v178 offset:21504
	ds_read_b128 v[214:217], v178 offset:22528
	ds_read_b128 v[218:221], v178 offset:23552
	v_lshl_add_u64 v[222:223], s[46:47], 0, v[0:1]
	global_load_lds_dwordx4 v[222:223], off
	s_add_i32 m0, s22, 0x2000
	s_add_u32 s22, s46, 0x160000
	v_lshl_add_u64 v[224:225], s[46:47], 0, v[158:159]
	s_addc_u32 s23, s47, 0
	s_add_i32 s50, s51, s16
	global_load_lds_dwordx4 v[224:225], off
	s_mov_b32 m0, s50
	v_lshl_add_u64 v[228:229], s[48:49], 0, v[160:161]
	global_load_lds_dwordx4 v0, s[22:23]
	s_add_i32 m0, s50, 0x2000
	s_nop 0
	global_load_lds_dwordx4 v158, s[22:23]
	v_lshl_add_u64 v[226:227], s[48:49], 0, v[162:163]
	s_mov_b32 m0, s33
	s_nop 0
	global_load_lds_dwordx4 v[226:227], off
	s_mov_b32 m0, s37
	s_nop 0
	global_load_lds_dwordx4 v[228:229], off
	s_waitcnt vmcnt(8) lgkmcnt(0)
	s_barrier
	v_mfma_f32_16x16x32_bf16 v[78:81], v[42:45], v[184:187], v[78:81]
	v_mfma_f32_16x16x32_bf16 v[74:77], v[50:53], v[184:187], v[74:77]
	v_mfma_f32_16x16x32_bf16 v[62:65], v[42:45], v[192:195], v[62:65]
	v_mfma_f32_16x16x32_bf16 v[58:61], v[50:53], v[192:195], v[58:61]
	v_mfma_f32_16x16x32_bf16 v[30:33], v[42:45], v[200:203], v[30:33]
	v_mfma_f32_16x16x32_bf16 v[26:29], v[50:53], v[200:203], v[26:29]
	v_mfma_f32_16x16x32_bf16 v[14:17], v[42:45], v[214:217], v[14:17]
	v_mfma_f32_16x16x32_bf16 v[10:13], v[50:53], v[214:217], v[10:13]
	v_mfma_f32_16x16x32_bf16 v[78:81], v[46:49], v[188:191], v[78:81]
	v_mfma_f32_16x16x32_bf16 v[74:77], v[54:57], v[188:191], v[74:77]
	v_mfma_f32_16x16x32_bf16 v[62:65], v[46:49], v[196:199], v[62:65]
	v_mfma_f32_16x16x32_bf16 v[58:61], v[54:57], v[196:199], v[58:61]
	v_mfma_f32_16x16x32_bf16 v[30:33], v[46:49], v[210:213], v[30:33]
	v_mfma_f32_16x16x32_bf16 v[26:29], v[54:57], v[210:213], v[26:29]
	v_mfma_f32_16x16x32_bf16 v[14:17], v[46:49], v[218:221], v[14:17]
	v_mfma_f32_16x16x32_bf16 v[10:13], v[54:57], v[218:221], v[10:13]
	v_mfma_f32_16x16x32_bf16 v[38:41], v[154:157], v[192:195], v[38:41]
	v_mfma_f32_16x16x32_bf16 v[34:37], v[172:175], v[192:195], v[34:37]
	v_mfma_f32_16x16x32_bf16 v[22:25], v[154:157], v[200:203], v[22:25]
	v_mfma_f32_16x16x32_bf16 v[18:21], v[172:175], v[200:203], v[18:21]
	v_mfma_f32_16x16x32_bf16 v[6:9], v[154:157], v[214:217], v[6:9]
	v_mfma_f32_16x16x32_bf16 v[2:5], v[172:175], v[214:217], v[2:5]
	v_mfma_f32_16x16x32_bf16 v[42:45], v[154:157], v[184:187], v[70:73]
	v_mfma_f32_16x16x32_bf16 v[46:49], v[172:175], v[184:187], v[66:69]
	v_mfma_f32_16x16x32_bf16 v[38:41], v[168:171], v[196:199], v[38:41]
	v_mfma_f32_16x16x32_bf16 v[34:37], v[180:183], v[196:199], v[34:37]
	v_mfma_f32_16x16x32_bf16 v[22:25], v[168:171], v[210:213], v[22:25]
	v_mfma_f32_16x16x32_bf16 v[18:21], v[180:183], v[210:213], v[18:21]
	v_mfma_f32_16x16x32_bf16 v[6:9], v[168:171], v[218:221], v[6:9]
	v_mfma_f32_16x16x32_bf16 v[2:5], v[180:183], v[218:221], v[2:5]
	v_mfma_f32_16x16x32_bf16 v[42:45], v[168:171], v[188:191], v[42:45]
	v_mfma_f32_16x16x32_bf16 v[46:49], v[180:183], v[188:191], v[46:49]
	s_barrier
	s_add_i32 s50, 0, 0x18000
	s_add_i32 s51, 0, 0x1c000
	ds_read_b128 v[50:53], v238
	ds_read_b128 v[54:57], v238 offset:1024
	ds_read_b128 v[66:69], v238 offset:2048
	ds_read_b128 v[70:73], v238 offset:3072
	ds_read_b128 v[154:157], v239
	ds_read_b128 v[168:171], v239 offset:1024
	ds_read_b128 v[172:175], v239 offset:2048
	ds_read_b128 v[180:183], v239 offset:3072
	s_add_u32 s22, s48, 0x160000
	s_addc_u32 s23, s49, 0
	s_mov_b32 m0, s52
	ds_read_b128 v[184:187], v178 offset:32768
	ds_read_b128 v[188:191], v178 offset:33792
	ds_read_b128 v[192:195], v178 offset:34816
	ds_read_b128 v[196:199], v178 offset:35840
	ds_read_b128 v[200:203], v178 offset:36864
	ds_read_b128 v[210:213], v178 offset:37888
	ds_read_b128 v[214:217], v178 offset:38912
	ds_read_b128 v[218:221], v178 offset:39936
	global_load_lds_dwordx4 v162, s[22:23]
	s_mov_b32 m0, s53
	s_nop 0
	global_load_lds_dwordx4 v160, s[22:23]
	s_waitcnt vmcnt(8) lgkmcnt(0)
	s_barrier
	v_mfma_f32_16x16x32_bf16 v[142:145], v[50:53], v[184:187], v[142:145]
	v_mfma_f32_16x16x32_bf16 v[138:141], v[66:69], v[184:187], v[138:141]
	v_mfma_f32_16x16x32_bf16 v[126:129], v[50:53], v[192:195], v[126:129]
	v_mfma_f32_16x16x32_bf16 v[122:125], v[66:69], v[192:195], v[122:125]
	v_mfma_f32_16x16x32_bf16 v[110:113], v[50:53], v[200:203], v[110:113]
	v_mfma_f32_16x16x32_bf16 v[106:109], v[66:69], v[200:203], v[106:109]
	v_mfma_f32_16x16x32_bf16 v[94:97], v[50:53], v[214:217], v[94:97]
	v_mfma_f32_16x16x32_bf16 v[90:93], v[66:69], v[214:217], v[90:93]
	v_mfma_f32_16x16x32_bf16 v[142:145], v[54:57], v[188:191], v[142:145]
	v_mfma_f32_16x16x32_bf16 v[138:141], v[70:73], v[188:191], v[138:141]
	v_mfma_f32_16x16x32_bf16 v[126:129], v[54:57], v[196:199], v[126:129]
	v_mfma_f32_16x16x32_bf16 v[122:125], v[70:73], v[196:199], v[122:125]
	v_mfma_f32_16x16x32_bf16 v[110:113], v[54:57], v[210:213], v[110:113]
	v_mfma_f32_16x16x32_bf16 v[106:109], v[70:73], v[210:213], v[106:109]
	v_mfma_f32_16x16x32_bf16 v[94:97], v[54:57], v[218:221], v[94:97]
	v_mfma_f32_16x16x32_bf16 v[90:93], v[70:73], v[218:221], v[90:93]
	v_mfma_f32_16x16x32_bf16 v[134:137], v[154:157], v[184:187], v[134:137]
	v_mfma_f32_16x16x32_bf16 v[130:133], v[172:175], v[184:187], v[130:133]
	v_mfma_f32_16x16x32_bf16 v[118:121], v[154:157], v[192:195], v[118:121]
	v_mfma_f32_16x16x32_bf16 v[114:117], v[172:175], v[192:195], v[114:117]
	v_mfma_f32_16x16x32_bf16 v[102:105], v[154:157], v[200:203], v[102:105]
	v_mfma_f32_16x16x32_bf16 v[98:101], v[172:175], v[200:203], v[98:101]
	v_mfma_f32_16x16x32_bf16 v[86:89], v[154:157], v[214:217], v[86:89]
	v_mfma_f32_16x16x32_bf16 v[82:85], v[172:175], v[214:217], v[82:85]
	v_mfma_f32_16x16x32_bf16 v[134:137], v[168:171], v[188:191], v[134:137]
	v_mfma_f32_16x16x32_bf16 v[130:133], v[180:183], v[188:191], v[130:133]
	v_mfma_f32_16x16x32_bf16 v[118:121], v[168:171], v[196:199], v[118:121]
	v_mfma_f32_16x16x32_bf16 v[114:117], v[180:183], v[196:199], v[114:117]
	v_mfma_f32_16x16x32_bf16 v[102:105], v[168:171], v[210:213], v[102:105]
	v_mfma_f32_16x16x32_bf16 v[98:101], v[180:183], v[210:213], v[98:101]
	v_mfma_f32_16x16x32_bf16 v[86:89], v[168:171], v[218:221], v[86:89]
	v_mfma_f32_16x16x32_bf16 v[82:85], v[180:183], v[218:221], v[82:85]
	s_barrier
	s_add_i32 s22, s50, s16
	s_mov_b32 m0, s22
	ds_read_b128 v[184:187], v178 offset:49152
	ds_read_b128 v[188:191], v178 offset:50176
	ds_read_b128 v[192:195], v178 offset:51200
	ds_read_b128 v[196:199], v178 offset:52224
	ds_read_b128 v[200:203], v178 offset:53248
	ds_read_b128 v[210:213], v178 offset:54272
	ds_read_b128 v[214:217], v178 offset:55296
	ds_read_b128 v[218:221], v178 offset:56320
	v_lshl_add_u64 v[222:223], v[222:223], 0, s[34:35]
	global_load_lds_dwordx4 v[222:223], off
	s_add_i32 m0, s22, 0x2000
	s_add_u32 s22, s46, 0x160080
	v_lshl_add_u64 v[222:223], v[224:225], 0, s[34:35]
	s_addc_u32 s23, s47, 0
	s_add_i32 s46, s51, s16
	global_load_lds_dwordx4 v[222:223], off
	s_mov_b32 m0, s46
	s_nop 0
	global_load_lds_dwordx4 v0, s[22:23]
	s_add_i32 m0, s46, 0x2000
	s_nop 0
	global_load_lds_dwordx4 v158, s[22:23]
	v_lshl_add_u64 v[222:223], v[226:227], 0, s[34:35]
	s_mov_b32 m0, s55
	s_nop 0
	global_load_lds_dwordx4 v[222:223], off
	v_lshl_add_u64 v[222:223], v[228:229], 0, s[34:35]
	s_mov_b32 m0, s56
	s_nop 0
	global_load_lds_dwordx4 v[222:223], off
	s_waitcnt vmcnt(8) lgkmcnt(0)
	s_barrier
	v_mfma_f32_16x16x32_bf16 v[78:81], v[50:53], v[184:187], v[78:81]
	v_mfma_f32_16x16x32_bf16 v[74:77], v[66:69], v[184:187], v[74:77]
	v_mfma_f32_16x16x32_bf16 v[62:65], v[50:53], v[192:195], v[62:65]
	v_mfma_f32_16x16x32_bf16 v[58:61], v[66:69], v[192:195], v[58:61]
	v_mfma_f32_16x16x32_bf16 v[30:33], v[50:53], v[200:203], v[30:33]
	v_mfma_f32_16x16x32_bf16 v[26:29], v[66:69], v[200:203], v[26:29]
	v_mfma_f32_16x16x32_bf16 v[14:17], v[50:53], v[214:217], v[14:17]
	v_mfma_f32_16x16x32_bf16 v[10:13], v[66:69], v[214:217], v[10:13]
	v_mfma_f32_16x16x32_bf16 v[78:81], v[54:57], v[188:191], v[78:81]
	v_mfma_f32_16x16x32_bf16 v[74:77], v[70:73], v[188:191], v[74:77]
	v_mfma_f32_16x16x32_bf16 v[62:65], v[54:57], v[196:199], v[62:65]
	v_mfma_f32_16x16x32_bf16 v[58:61], v[70:73], v[196:199], v[58:61]
	v_mfma_f32_16x16x32_bf16 v[30:33], v[54:57], v[210:213], v[30:33]
	v_mfma_f32_16x16x32_bf16 v[26:29], v[70:73], v[210:213], v[26:29]
	v_mfma_f32_16x16x32_bf16 v[14:17], v[54:57], v[218:221], v[14:17]
	v_mfma_f32_16x16x32_bf16 v[10:13], v[70:73], v[218:221], v[10:13]
	v_mfma_f32_16x16x32_bf16 v[42:45], v[154:157], v[184:187], v[42:45]
	v_mfma_f32_16x16x32_bf16 v[70:73], v[168:171], v[188:191], v[42:45]
	v_mfma_f32_16x16x32_bf16 v[42:45], v[172:175], v[184:187], v[46:49]
	v_mfma_f32_16x16x32_bf16 v[38:41], v[154:157], v[192:195], v[38:41]
	v_mfma_f32_16x16x32_bf16 v[34:37], v[172:175], v[192:195], v[34:37]
	v_mfma_f32_16x16x32_bf16 v[22:25], v[154:157], v[200:203], v[22:25]
	v_mfma_f32_16x16x32_bf16 v[18:21], v[172:175], v[200:203], v[18:21]
	v_mfma_f32_16x16x32_bf16 v[6:9], v[154:157], v[214:217], v[6:9]
	v_mfma_f32_16x16x32_bf16 v[2:5], v[172:175], v[214:217], v[2:5]
	v_mfma_f32_16x16x32_bf16 v[66:69], v[180:183], v[188:191], v[42:45]
	v_mfma_f32_16x16x32_bf16 v[38:41], v[168:171], v[196:199], v[38:41]
	v_mfma_f32_16x16x32_bf16 v[34:37], v[180:183], v[196:199], v[34:37]
	v_mfma_f32_16x16x32_bf16 v[22:25], v[168:171], v[210:213], v[22:25]
	v_mfma_f32_16x16x32_bf16 v[18:21], v[180:183], v[210:213], v[18:21]
	v_mfma_f32_16x16x32_bf16 v[6:9], v[168:171], v[218:221], v[6:9]
	v_mfma_f32_16x16x32_bf16 v[2:5], v[180:183], v[218:221], v[2:5]
	s_barrier
	s_add_i32 s25, s25, 2
	s_add_u32 s18, s18, 0x100
	s_addc_u32 s19, s19, 0
	s_cmpk_gt_u32 s25, 0x55
	s_mov_b64 s[22:23], s[42:43]
	s_cbranch_scc0 .LBB0_728
	s_setprio 0
	s_and_b64 vcc, exec, s[12:13]
	s_cbranch_vccz .LBB0_731
	s_barrier
